# in-proj GEMM: column-tile index rotated by 12 so the half-empty 13th round holds cheap (raw) tiles and per-workgroup epilogue cost is more even
# speedup vs baseline: 1.0012x; 1.0012x over previous
;     __device__ bool next(int i, Unit& u) const {
;         int tile = i, seg = 0;
;         if (nseg == 3) { tile = i / 3; seg = i - tile * 3; }
;         const long L = (long)tile * G + c; if (L >= nwg) return false;
;         int wgid = (int)L; { const int q = nwg / NXCD, r = nwg % NXCD, xcd = wgid % NXCD, off = wgid / NXCD; wgid = (xcd < r ? xcd * (q + 1) : r * (q + 1) + (xcd - r) * q) + off; }
;         const int nig = WGM * nN, gid = wgid / nig, fm = gid * WGM, gsz = (nM - fm) < WGM ? (nM - fm) : WGM;
;         u.pm = fm + ((wgid % nig) % gsz); u.pn = (wgid % nig) / gsz; u.seg = seg;
.LBB0_223:
	s_or_b64 exec, exec, s[8:9]
	s_load_dwordx4 s[12:15], s[4:5], 0x20
	s_load_dwordx2 s[18:19], s[4:5], 0x30
	s_cmpk_lt_i32 s70, 0xc80
	s_cselect_b64 s[4:5], -1, 0
	s_cmpk_gt_i32 s70, 0xc7f
	v_readfirstlane_b32 s11, v130
	s_cbranch_scc1 .LBB0_225
	s_ashr_i32 s8, s70, 31
	s_lshr_b32 s8, s8, 29
	s_add_i32 s8, s70, s8
	s_ashr_i32 s9, s8, 3
	s_and_b32 s8, s8, -8
	s_sub_i32 s8, s70, s8
	s_cmp_lt_i32 s8, 0
	s_movk_i32 s22, 0x191
	s_cselect_b32 s22, s22, 0x190
	s_mul_i32 s8, s8, s22
	s_add_i32 s8, s8, s9
	s_mul_hi_i32 s9, s8, 0x51eb851f
	s_lshr_b32 s22, s9, 31
	s_ashr_i32 s9, s9, 5
	s_add_i32 s9, s9, s22
	s_lshl_b32 s22, s9, 2
	s_mulk_i32 s9, 0x64
	s_sub_i32 s8, s8, s9
	s_bfe_i32 s9, s8, 0x80000
	s_bfe_u32 s9, s9, 0x2000d
	s_add_i32 s9, s8, s9
	s_bfe_i32 s23, s9, 0x80000
	s_and_b32 s9, s9, 0xfc
	s_sub_i32 s8, s8, s9
	s_sext_i32_i16 s23, s23
	s_sext_i32_i8 s8, s8
	s_add_i32 s66, s22, s8
	s_ashr_i32 s8, s23, 2
	s_add_i32 s8, s8, 12
	s_cmp_ge_i32 s8, 25
	s_cselect_b32 s95, 25, 0
	s_sub_i32 s8, s8, s95

;     __device__ bool next(int i, Unit& u) const {
;         int tile = i, seg = 0;
;         if (nseg == 3) { tile = i / 3; seg = i - tile * 3; }
;         const long L = (long)tile * G + c; if (L >= nwg) return false;
;         int wgid = (int)L; { const int q = nwg / NXCD, r = nwg % NXCD, xcd = wgid % NXCD, off = wgid / NXCD; wgid = (xcd < r ? xcd * (q + 1) : r * (q + 1) + (xcd - r) * q) + off; }
;         const int nig = WGM * nN, gid = wgid / nig, fm = gid * WGM, gsz = (nM - fm) < WGM ? (nM - fm) : WGM;
;         u.pm = fm + ((wgid % nig) % gsz); u.pn = (wgid % nig) / gsz; u.seg = seg;
.LBB0_236:
	s_add_i32 s11, s9, 1
	s_mul_i32 s6, s11, s90
	s_mul_hi_u32 s7, s11, s21
	s_add_i32 s7, s7, s6
	s_mul_i32 s6, s11, s21
	s_add_u32 s58, s6, s70
	s_addc_u32 s59, s7, s96
	v_cmp_gt_i64_e32 vcc, s[58:59], v[154:155]
	v_cmp_lt_i64_e64 s[6:7], s[58:59], v[152:153]
	s_cbranch_vccnz .LBB0_238
	s_ashr_i32 s26, s58, 31
	s_lshr_b32 s26, s26, 29
	s_add_i32 s26, s58, s26
	s_ashr_i32 s27, s26, 3
	s_and_b32 s26, s26, -8
	s_sub_i32 s26, s58, s26
	s_cmp_lt_i32 s26, 0
	s_movk_i32 s28, 0x191
	s_cselect_b32 s28, s28, 0x190
	s_mul_i32 s26, s26, s28
	s_add_i32 s26, s26, s27
	s_mul_hi_i32 s27, s26, 0x51eb851f
	s_lshr_b32 s28, s27, 31
	s_ashr_i32 s27, s27, 5
	s_add_i32 s27, s27, s28
	s_lshl_b32 s28, s27, 2
	s_sub_i32 s54, 0x80, s28
	s_min_i32 s55, s54, 4
	s_abs_i32 s54, s55
	v_cvt_f32_u32_e32 v0, s54
	s_sub_i32 s57, 0, s54
	s_mulk_i32 s27, 0x64
	s_sub_i32 s26, s26, s27
	v_rcp_iflag_f32_e32 v0, v0
	s_abs_i32 s27, s26
	s_xor_b32 s56, s26, s55
	s_ashr_i32 s56, s56, 31
	v_mul_f32_e32 v0, 0x4f7ffffe, v0
	v_cvt_u32_f32_e32 v0, v0
	s_nop 0
	v_readfirstlane_b32 s58, v0
	s_mul_i32 s57, s57, s58
	s_mul_hi_u32 s57, s58, s57
	s_add_i32 s58, s58, s57
	s_mul_hi_u32 s57, s27, s58
	s_mul_i32 s58, s57, s54
	s_sub_i32 s27, s27, s58
	s_add_i32 s59, s57, 1
	s_sub_i32 s58, s27, s54
	s_cmp_ge_u32 s27, s54
	s_cselect_b32 s57, s59, s57
	s_cselect_b32 s27, s58, s27
	s_add_i32 s58, s57, 1
	s_cmp_ge_u32 s27, s54
	s_cselect_b32 s27, s58, s57
	s_xor_b32 s27, s27, s56
	s_sub_i32 s54, s27, s56
	s_mul_i32 s27, s54, s55
	s_sub_i32 s26, s26, s27
	s_add_i32 s56, s28, s26
	s_add_i32 s54, s54, 12
	s_cmp_ge_i32 s54, 25
	s_cselect_b32 s95, 25, 0
	s_sub_i32 s54, s54, s95
